# LDS-DMA issue interleaved between the QK MFMAs instead of at the head of the step
# speedup vs baseline: 1.0475x; 1.0135x over previous
; template <int KB> __device__ __forceinline__ void qkt_half(f32x16& p, const char* K_lds, int r32, int hi, int kh, const char* qf, bf16x8 q0) {
;     p = f32x16{};
;     const char* kb[4];
; #pragma unroll
;     for (int dd = 0; dd < 4; ++dd) kb[dd] = K_lds + KB * SHM_K + kh * 8192 + KSWZ(r32, (dd * 16 + hi * 8) * 2);
; #pragma unroll
;     for (int d0 = 0; d0 < 8; ++d0) { const bf16x8 b0 = *reinterpret_cast<const bf16x8*>(kb[d0 & 3] + (d0 >> 2) * 128); const bf16x8 q = d0 == 0 ? q0 : *reinterpret_cast<const bf16x8*>(qf + (d0 - 1) * 1024); p = __builtin_amdgcn_mfma_f32_32x32x16_bf16(b0, q, p, 0, 0, 0); }
; }
.LBB0_369:
	ds_read_b128 v[184:187], v220 offset:16384
	ds_read_b128 v[180:183], v220 offset:17408
	ds_read_b128 v[64:67], v211
	ds_read_b128 v[68:71], v212
	ds_read_b128 v[72:75], v213
	ds_read_b128 v[76:79], v214
	ds_read_b128 v[80:83], v211 offset:128
	ds_read_b128 v[84:87], v212 offset:128
	ds_read_b128 v[88:91], v213 offset:128
	ds_read_b128 v[92:95], v214 offset:128
	s_waitcnt lgkmcnt(7)
	v_mfma_f32_32x32x16_bf16 v[128:143], v[64:67], v[144:147], 0
	s_waitcnt lgkmcnt(6)
	v_mfma_f32_32x32x16_bf16 v[128:143], v[68:71], v[148:151], v[128:143]
	s_add_i32 s90, s87, -3
	s_cmp_gt_u32 s90, s84
	s_cbranch_scc1 .Ld0_h1_noK
	s_add_i32 s90, s87, -2
	s_cmp_lg_u64 s[46:47], 0
	s_cselect_b32 s90, s90, s53
	s_lshl_b32 s90, s90, 14
	s_add_u32 s92, s98, s90
	s_addc_u32 s93, s99, 0
	s_add_i32 m0, s100, 0x14000
	s_nop 0
	global_load_lds_dwordx4 v250, s[92:93]
	s_add_u32 s92, s92, 0x2000
	s_addc_u32 s93, s93, 0
	s_add_i32 m0, s100, 0x16000
	s_nop 0
	global_load_lds_dwordx4 v250, s[92:93]
.Ld0_h1_noK:
	s_waitcnt lgkmcnt(5)
	v_mfma_f32_32x32x16_bf16 v[128:143], v[72:75], v[152:155], v[128:143]
	s_waitcnt lgkmcnt(4)
	v_mfma_f32_32x32x16_bf16 v[128:143], v[76:79], v[156:159], v[128:143]
	s_add_i32 s90, s87, -3
	s_add_i32 s91, s53, 1
	s_cmp_lg_u64 s[46:47], 0
	s_cselect_b32 s90, s90, s91
	s_lshl_b32 s90, s90, 14
	s_add_u32 s92, s8, s90
	s_addc_u32 s93, s9, 0
	s_mov_b32 m0, s100
	s_nop 0
	global_load_lds_dwordx4 v251, s[92:93]
	s_add_u32 s92, s92, 0x2000
	s_addc_u32 s93, s93, 0
	s_add_i32 m0, s100, 0x2000
	s_nop 0
	global_load_lds_dwordx4 v251, s[92:93]
	s_waitcnt lgkmcnt(3)
	v_mfma_f32_32x32x16_bf16 v[128:143], v[80:83], v[160:163], v[128:143]
	s_waitcnt lgkmcnt(2)
	v_mfma_f32_32x32x16_bf16 v[128:143], v[84:87], v[164:167], v[128:143]
	s_add_u32 s92, s12, s90
	s_addc_u32 s93, s13, 0
	s_add_i32 m0, s100, 0x4000
	s_nop 0
	global_load_lds_dwordx4 v251, s[92:93]
	s_add_u32 s92, s92, 0x2000
	s_addc_u32 s93, s93, 0
	s_add_i32 m0, s100, 0x6000
	s_nop 0
	global_load_lds_dwordx4 v251, s[92:93]
	s_waitcnt lgkmcnt(1)
	v_mfma_f32_32x32x16_bf16 v[128:143], v[88:91], v[168:171], v[128:143]
	s_waitcnt lgkmcnt(0)
	v_mfma_f32_32x32x16_bf16 v[128:143], v[92:95], v[252:255], v[128:143]
	s_mov_b64 s[4:5], -1
	s_and_b64 vcc, exec, s[48:49]
	s_cbranch_vccz .LBB0_371
	ds_read_b64_tr_b16 v[80:81], v194 offset:0xc000
	ds_read_b64_tr_b16 v[82:83], v194 offset:0xc800
	ds_read_b64_tr_b16 v[84:85], v194 offset:0xd000
	ds_read_b64_tr_b16 v[86:87], v194 offset:0xd800
	ds_read_b64_tr_b16 v[88:89], v194 offset:0xe000
	ds_read_b64_tr_b16 v[90:91], v194 offset:0xe800
	ds_read_b64_tr_b16 v[92:93], v194 offset:0xf000
	ds_read_b64_tr_b16 v[94:95], v194 offset:0xf800
	s_waitcnt lgkmcnt(0)
	s_nop 0
	v_mfma_f32_32x32x16_bf16 v[64:79], v[184:187], v[80:83], v[0:15]
	ds_read_b64_tr_b16 v[96:97], v194 offset:0xc200
	ds_read_b64_tr_b16 v[98:99], v194 offset:0xca00
	ds_read_b64_tr_b16 v[100:101], v194 offset:0xd200
	ds_read_b64_tr_b16 v[102:103], v194 offset:0xda00
	ds_read_b64_tr_b16 v[104:105], v194 offset:0xe200
	ds_read_b64_tr_b16 v[106:107], v194 offset:0xea00
	ds_read_b64_tr_b16 v[108:109], v194 offset:0xf200
	v_mfma_f32_32x32x16_bf16 v[64:79], v[180:183], v[84:87], v[64:79]
	ds_read_b64_tr_b16 v[110:111], v194 offset:0xfa00
	v_mfma_f32_32x32x16_bf16 v[64:79], v[172:175], v[88:91], v[64:79]
	v_mfma_f32_32x32x16_bf16 v[64:79], v[176:179], v[92:95], v[64:79]
	s_waitcnt lgkmcnt(0)
	v_mfma_f32_32x32x16_bf16 v[80:95], v[184:187], v[96:99], v[16:31]
	ds_read_b64_tr_b16 v[112:113], v194 offset:0xc400
	ds_read_b64_tr_b16 v[114:115], v194 offset:0xcc00
	ds_read_b64_tr_b16 v[116:117], v194 offset:0xd400
	ds_read_b64_tr_b16 v[118:119], v194 offset:0xdc00
	ds_read_b64_tr_b16 v[120:121], v194 offset:0xe400
	ds_read_b64_tr_b16 v[122:123], v194 offset:0xec00
	ds_read_b64_tr_b16 v[124:125], v194 offset:0xf400
	v_mfma_f32_32x32x16_bf16 v[80:95], v[180:183], v[100:103], v[80:95]
	ds_read_b64_tr_b16 v[126:127], v194 offset:0xfc00
	s_add_i32 s38, s87, -3
	s_add_i32 s50, s53, 1
	s_and_b64 s[4:5], s[46:47], exec
	s_cselect_b32 s4, s38, s50
	s_lshl_b32 s4, s4, 6
	s_cmp_le_i32 s4, s86
	s_cbranch_scc0 .Lm0_h1B_mk

; template <int KB> __device__ __forceinline__ void qkt_half(f32x16& p, const char* K_lds, int r32, int hi, int kh, const char* qf, bf16x8 q0) {
;     p = f32x16{};
;     const char* kb[4];
; #pragma unroll
;     for (int dd = 0; dd < 4; ++dd) kb[dd] = K_lds + KB * SHM_K + kh * 8192 + KSWZ(r32, (dd * 16 + hi * 8) * 2);
; #pragma unroll
;     for (int d0 = 0; d0 < 8; ++d0) { const bf16x8 b0 = *reinterpret_cast<const bf16x8*>(kb[d0 & 3] + (d0 >> 2) * 128); const bf16x8 q = d0 == 0 ? q0 : *reinterpret_cast<const bf16x8*>(qf + (d0 - 1) * 1024); p = __builtin_amdgcn_mfma_f32_32x32x16_bf16(b0, q, p, 0, 0, 0); }
; }
.LBB0_377:
	s_waitcnt vmcnt(0) lgkmcnt(0)
	s_barrier
	ds_read_b32 v1, v197
	v_max_f32_e32 v0, v0, v0
	v_mov_b32_e32 v230, 1.0
	s_waitcnt lgkmcnt(0)
	v_max_f32_e32 v1, v1, v1
	v_max_f32_e32 v0, v0, v1
	v_sub_f32_e32 v1, v0, v218
	v_mul_f32_e32 v1, 0x3db504f3, v1
	v_cmp_ge_f32_e32 vcc, s72, v1
	s_cmp_eq_u64 vcc, exec
	s_cbranch_scc0 .LBB0_403
.LBB0_386:
	ds_read_b128 v[184:187], v220
	ds_read_b128 v[180:183], v220 offset:1024
	ds_read_b128 v[0:3], v222
	ds_read_b128 v[4:7], v223
	ds_read_b128 v[8:11], v224
	ds_read_b128 v[12:15], v225
	ds_read_b128 v[16:19], v222 offset:128
	ds_read_b128 v[20:23], v223 offset:128
	ds_read_b128 v[24:27], v224 offset:128
	ds_read_b128 v[28:31], v225 offset:128
	s_waitcnt lgkmcnt(7)
	v_mfma_f32_32x32x16_bf16 v[128:143], v[0:3], v[144:147], 0
	s_waitcnt lgkmcnt(6)
	v_mfma_f32_32x32x16_bf16 v[128:143], v[4:7], v[148:151], v[128:143]
	s_add_i32 s90, s87, -1
	s_cmp_gt_u32 s90, s85
	s_cbranch_scc1 .Ld0_h2_noK
	s_add_i32 s91, s53, -1
	s_cmp_lg_u64 s[46:47], 0
	s_cselect_b32 s90, s90, s91
	s_lshl_b32 s90, s90, 14
	s_add_u32 s92, s98, s90
	s_addc_u32 s93, s99, 0
	s_add_i32 m0, s100, 0x10000
	s_nop 0
	global_load_lds_dwordx4 v250, s[92:93]
	s_add_u32 s92, s92, 0x2000
	s_addc_u32 s93, s93, 0
	s_add_i32 m0, s100, 0x12000
	s_nop 0
	global_load_lds_dwordx4 v250, s[92:93]
.Ld0_h2_noK:
	s_waitcnt lgkmcnt(5)
	v_mfma_f32_32x32x16_bf16 v[128:143], v[8:11], v[152:155], v[128:143]
	s_waitcnt lgkmcnt(4)
	v_mfma_f32_32x32x16_bf16 v[128:143], v[12:15], v[156:159], v[128:143]
	s_add_i32 s90, s87, -2
	s_cmp_lg_u64 s[46:47], 0
	s_cselect_b32 s90, s90, s53
	s_lshl_b32 s90, s90, 14
	s_add_u32 s92, s8, s90
	s_addc_u32 s93, s9, 0
	s_add_i32 m0, s100, 0x8000
	s_nop 0
	global_load_lds_dwordx4 v251, s[92:93]
	s_add_u32 s92, s92, 0x2000
	s_addc_u32 s93, s93, 0
	s_add_i32 m0, s100, 0xa000
	s_nop 0
	global_load_lds_dwordx4 v251, s[92:93]
	s_waitcnt lgkmcnt(3)
	v_mfma_f32_32x32x16_bf16 v[128:143], v[16:19], v[160:163], v[128:143]
	s_waitcnt lgkmcnt(2)
	v_mfma_f32_32x32x16_bf16 v[128:143], v[20:23], v[164:167], v[128:143]
	s_add_u32 s92, s12, s90
	s_addc_u32 s93, s13, 0
	s_add_i32 m0, s100, 0xc000
	s_nop 0
	global_load_lds_dwordx4 v251, s[92:93]
	s_add_u32 s92, s92, 0x2000
	s_addc_u32 s93, s93, 0
	s_add_i32 m0, s100, 0xe000
	s_nop 0
	global_load_lds_dwordx4 v251, s[92:93]
	s_waitcnt lgkmcnt(1)
	v_mfma_f32_32x32x16_bf16 v[128:143], v[24:27], v[168:171], v[128:143]
	s_waitcnt lgkmcnt(0)
	v_mfma_f32_32x32x16_bf16 v[128:143], v[28:31], v[252:255], v[128:143]
	s_mov_b64 s[4:5], -1
	s_and_b64 vcc, exec, s[48:49]
	s_cbranch_vccz .LBB0_388
	ds_read_b64_tr_b16 v[16:17], v194 offset:0x4000
	ds_read_b64_tr_b16 v[18:19], v194 offset:0x4800
	ds_read_b64_tr_b16 v[20:21], v194 offset:0x5000
	ds_read_b64_tr_b16 v[22:23], v194 offset:0x5800
	ds_read_b64_tr_b16 v[24:25], v194 offset:0x6000
	ds_read_b64_tr_b16 v[26:27], v194 offset:0x6800
	ds_read_b64_tr_b16 v[28:29], v194 offset:0x7000
	ds_read_b64_tr_b16 v[30:31], v194 offset:0x7800
	s_waitcnt lgkmcnt(0)
	s_nop 0
	v_mfma_f32_32x32x16_bf16 v[0:15], v[184:187], v[16:19], v[64:79]
	ds_read_b64_tr_b16 v[32:33], v194 offset:0x4200
	ds_read_b64_tr_b16 v[34:35], v194 offset:0x4a00
	ds_read_b64_tr_b16 v[36:37], v194 offset:0x5200
	ds_read_b64_tr_b16 v[38:39], v194 offset:0x5a00
	ds_read_b64_tr_b16 v[40:41], v194 offset:0x6200
	ds_read_b64_tr_b16 v[42:43], v194 offset:0x6a00
	ds_read_b64_tr_b16 v[44:45], v194 offset:0x7200
	v_mfma_f32_32x32x16_bf16 v[0:15], v[180:183], v[20:23], v[0:15]
	ds_read_b64_tr_b16 v[46:47], v194 offset:0x7a00
	v_mfma_f32_32x32x16_bf16 v[0:15], v[172:175], v[24:27], v[0:15]
	v_mfma_f32_32x32x16_bf16 v[0:15], v[176:179], v[28:31], v[0:15]
	s_waitcnt lgkmcnt(0)
	v_mfma_f32_32x32x16_bf16 v[16:31], v[184:187], v[32:35], v[80:95]
	ds_read_b64_tr_b16 v[48:49], v194 offset:0x4400
	ds_read_b64_tr_b16 v[50:51], v194 offset:0x4c00
	ds_read_b64_tr_b16 v[52:53], v194 offset:0x5400
	ds_read_b64_tr_b16 v[54:55], v194 offset:0x5c00
	ds_read_b64_tr_b16 v[56:57], v194 offset:0x6400
	ds_read_b64_tr_b16 v[58:59], v194 offset:0x6c00
	ds_read_b64_tr_b16 v[60:61], v194 offset:0x7400
	v_mfma_f32_32x32x16_bf16 v[16:31], v[180:183], v[36:39], v[16:31]
	ds_read_b64_tr_b16 v[62:63], v194 offset:0x7c00
	s_and_b64 s[4:5], s[46:47], exec
	s_cselect_b32 s4, s89, s53
	s_lshl_b32 s4, s4, 6
	s_cmp_le_i32 s4, s86
	s_cbranch_scc0 .Lm0_h2B_mk
